# v17 plus prologue transposer no longer waits for the next item loads, q_pe rope cos/sin loads issued together
# baseline (speedup 1.0000x reference)
.LBB2_98:
	s_or_b64 exec, exec, s[2:3]
	s_and_saveexec_b64 s[2:3], vcc
	s_cbranch_execz .LBB2_165
	s_movk_i32 s0, 0x2100
	v_mul_lo_u32 v34, v42, s0
	v_add_u32_e32 v36, 0, v34
	v_readlane_b32 s0, v252, 1
	v_lshlrev_b32_e32 v34, 3, v35
	s_lshl_b32 s27, s0, 3
	v_and_b32_e32 v82, 28, v43
	v_and_b32_e32 v34, 56, v34
	v_lshl_add_u32 v37, v82, 2, v36
	v_mul_u32_u24_e32 v38, 0x84, v66
	v_mul_u32_u24_e32 v35, 0x84, v34
	v_lshlrev_b32_e32 v39, 2, v66
	s_add_u32 s30, s12, 0x1f800000
	v_mov_b32_e32 v85, 0
	v_or_b32_e32 v86, 8, v66
	v_or_b32_e32 v88, 16, v66
	v_or_b32_e32 v90, 24, v66
	v_or_b32_e32 v92, 32, v66
	v_or_b32_e32 v96, 40, v66
	v_or_b32_e32 v98, 48, v66
	v_or_b32_e32 v100, 56, v66
	v_add3_u32 v71, v36, v35, v39
	s_addc_u32 s31, s13, 0
	s_mov_b64 s[34:35], 0
	s_movk_i32 s28, 0x23bf
	s_movk_i32 s29, 0x27bf
	s_movk_i32 s33, 0x2bbf
	s_movk_i32 s64, 0x33bf
	s_movk_i32 s65, 0x53bf
	s_mov_b64 s[36:37], 0x5480000
	s_mov_b64 s[38:39], 0x3480000
	s_mov_b64 s[40:41], 0x2c80000
	s_mov_b64 s[42:43], 0x2880000
	s_mov_b64 s[44:45], 0x2480000
	s_mov_b64 s[46:47], 0x2280000
	s_mov_b64 s[48:49], 0x2100000
	s_mov_b32 s66, 0x4080000
	s_movk_i32 s67, 0x80
	s_movk_i32 s68, 0x380
	s_movk_i32 s69, 0x43f
	s_movk_i32 s70, 0x2aab
	s_movk_i32 s71, 0x7f
	s_movk_i32 s72, 0x9f
	s_movk_i32 s73, 0x3e0
	v_add_u32_e32 v73, v37, v38
	v_lshlrev_b32_e32 v104, 1, v34
	v_mov_b32_e32 v75, 30
	v_mov_b32_e32 v77, 5
	v_mov_b32_e32 v79, 6
	v_readlane_b32 s1, v252, 2
	s_waitcnt vmcnt(0)
	s_branch .LBB2_102

.LBB2_101:
	s_or_b64 exec, exec, s[0:1]
	v_pk_mul_f32 v[4:5], v[72:73], v[4:5] op_sel_hi:[0,1]
	v_pk_mul_f32 v[2:3], v[72:73], v[2:3] op_sel_hi:[0,1]
	ds_write2_b32 v73, v2, v3 offset1:1
	ds_write2_b32 v73, v4, v5 offset0:2 offset1:3
	v_pk_mul_f32 v[4:5], v[70:71], v[6:7] op_sel_hi:[0,1]
	v_add_u32_e32 v6, 0x420, v73
	v_pk_mul_f32 v[2:3], v[70:71], v[8:9] op_sel_hi:[0,1]
	ds_write2_b32 v6, v4, v5 offset1:1
	v_add_u32_e32 v4, 0x428, v73
	ds_write2_b32 v4, v2, v3 offset1:1
	v_pk_mul_f32 v[4:5], v[76:77], v[10:11] op_sel_hi:[0,1]
	v_add_u32_e32 v6, 0x840, v73
	v_pk_mul_f32 v[2:3], v[76:77], v[12:13] op_sel_hi:[0,1]
	ds_write2_b32 v6, v4, v5 offset1:1
	v_add_u32_e32 v4, 0x848, v73
	ds_write2_b32 v4, v2, v3 offset1:1
	v_pk_mul_f32 v[4:5], v[74:75], v[14:15] op_sel_hi:[0,1]
	v_add_u32_e32 v6, 0xc60, v73
	v_pk_mul_f32 v[2:3], v[74:75], v[16:17] op_sel_hi:[0,1]
	ds_write2_b32 v6, v4, v5 offset1:1
	v_add_u32_e32 v4, 0xc68, v73
	ds_write2_b32 v4, v2, v3 offset1:1
	v_pk_mul_f32 v[4:5], v[80:81], v[18:19] op_sel_hi:[0,1]
	v_add_u32_e32 v6, 0x1080, v73
	v_pk_mul_f32 v[2:3], v[80:81], v[20:21] op_sel_hi:[0,1]
	ds_write2_b32 v6, v4, v5 offset1:1
	v_add_u32_e32 v4, 0x1088, v73
	ds_write2_b32 v4, v2, v3 offset1:1
	v_pk_mul_f32 v[4:5], v[78:79], v[22:23] op_sel_hi:[0,1]
	v_add_u32_e32 v6, 0x14a0, v73
	v_pk_mul_f32 v[2:3], v[78:79], v[24:25] op_sel_hi:[0,1]
	ds_write2_b32 v6, v4, v5 offset1:1
	v_add_u32_e32 v4, 0x14a8, v73
	ds_write2_b32 v4, v2, v3 offset1:1
	v_pk_mul_f32 v[4:5], v[102:103], v[26:27] op_sel_hi:[0,1]
	v_add_u32_e32 v6, 0x18c0, v73
	v_pk_mul_f32 v[2:3], v[102:103], v[28:29] op_sel_hi:[0,1]
	ds_write2_b32 v6, v4, v5 offset1:1
	v_add_u32_e32 v4, 0x18c8, v73
	ds_write2_b32 v4, v2, v3 offset1:1
	v_pk_mul_f32 v[4:5], v[94:95], v[30:31] op_sel_hi:[0,1]
	v_add_u32_e32 v6, 0x1ce0, v73
	v_pk_mul_f32 v[2:3], v[94:95], v[32:33] op_sel_hi:[0,1]
	ds_write2_b32 v6, v4, v5 offset1:1
	v_add_u32_e32 v4, 0x1ce8, v73
	ds_write2_b32 v4, v2, v3 offset1:1
	s_waitcnt lgkmcnt(0)
	ds_read2_b32 v[2:3], v71 offset1:33
	s_waitcnt lgkmcnt(0)
	v_cvt_pk_bf16_f32 v2, v2, v3
	ds_read2_b32 v[4:5], v71 offset0:66 offset1:99
	v_mov_b32_e32 v105, v85
	s_waitcnt lgkmcnt(0)
	v_cvt_pk_bf16_f32 v3, v4, v5
	ds_read2_b32 v[4:5], v71 offset0:132 offset1:165
	v_lshl_add_u64 v[8:9], v[68:69], 0, v[104:105]
	v_mad_i64_i32 v[10:11], s[0:1], v67, v66, 0
	s_waitcnt lgkmcnt(0)
	v_cvt_pk_bf16_f32 v4, v4, v5
	ds_read2_b32 v[6:7], v71 offset0:198 offset1:231
	s_waitcnt lgkmcnt(0)
	v_cvt_pk_bf16_f32 v5, v6, v7
	v_lshl_add_u64 v[10:11], v[10:11], 1, v[8:9]
	ds_read2_b32 v[6:7], v71 offset0:8 offset1:41
	global_store_dwordx4 v[10:11], v[2:5], off nt
	v_mad_i64_i32 v[10:11], s[0:1], v67, v86, 0
	s_waitcnt lgkmcnt(0)
	v_cvt_pk_bf16_f32 v2, v6, v7
	ds_read2_b32 v[4:5], v71 offset0:74 offset1:107
	s_waitcnt lgkmcnt(0)
	v_cvt_pk_bf16_f32 v3, v4, v5
	ds_read2_b32 v[4:5], v71 offset0:140 offset1:173
	s_waitcnt lgkmcnt(0)
	v_cvt_pk_bf16_f32 v4, v4, v5
	ds_read2_b32 v[6:7], v71 offset0:206 offset1:239
	s_waitcnt lgkmcnt(0)
	v_cvt_pk_bf16_f32 v5, v6, v7
	v_lshl_add_u64 v[10:11], v[10:11], 1, v[8:9]
	ds_read2_b32 v[6:7], v71 offset0:16 offset1:49
	global_store_dwordx4 v[10:11], v[2:5], off nt
	v_mad_i64_i32 v[10:11], s[0:1], v67, v88, 0
	s_waitcnt lgkmcnt(0)
	v_cvt_pk_bf16_f32 v2, v6, v7
	ds_read2_b32 v[4:5], v71 offset0:82 offset1:115
	s_waitcnt lgkmcnt(0)
	v_cvt_pk_bf16_f32 v3, v4, v5
	ds_read2_b32 v[4:5], v71 offset0:148 offset1:181
	s_waitcnt lgkmcnt(0)
	v_cvt_pk_bf16_f32 v4, v4, v5
	ds_read2_b32 v[6:7], v71 offset0:214 offset1:247
	s_waitcnt lgkmcnt(0)
	v_cvt_pk_bf16_f32 v5, v6, v7
	v_lshl_add_u64 v[10:11], v[10:11], 1, v[8:9]
	ds_read2_b32 v[6:7], v71 offset0:24 offset1:57
	global_store_dwordx4 v[10:11], v[2:5], off nt
	v_mov_b64_e32 v[68:69], v[106:107]
	s_waitcnt lgkmcnt(0)
	v_cvt_pk_bf16_f32 v2, v6, v7
	ds_read2_b32 v[4:5], v71 offset0:90 offset1:123
	s_waitcnt lgkmcnt(0)
	v_cvt_pk_bf16_f32 v3, v4, v5
	ds_read2_b32 v[4:5], v71 offset0:156 offset1:189
	s_waitcnt lgkmcnt(0)
	v_cvt_pk_bf16_f32 v4, v4, v5
	ds_read2_b32 v[6:7], v71 offset0:222 offset1:255
	s_waitcnt lgkmcnt(0)
	v_cvt_pk_bf16_f32 v5, v6, v7
	v_mad_i64_i32 v[6:7], s[0:1], v67, v90, 0
	v_lshl_add_u64 v[6:7], v[6:7], 1, v[8:9]
	global_store_dwordx4 v[6:7], v[2:5], off nt
	s_waitcnt lgkmcnt(0)
	s_waitcnt vmcnt(4)
	v_mov_b32_e32 v72, v83
	v_mov_b32_e32 v67, v99
	v_mov_b32_e32 v70, v87
	v_mov_b32_e32 v76, v81
	v_mov_b32_e32 v74, v89
	v_mov_b32_e32 v80, v93
	v_mov_b32_e32 v78, v95
	v_mov_b32_e32 v102, v91
	v_mov_b32_e32 v94, v97
	v_mov_b32_e32 v2, v34
	v_mov_b32_e32 v3, v35
	v_mov_b32_e32 v4, v36
	v_mov_b32_e32 v5, v37
	v_mov_b32_e32 v6, v38
	v_mov_b32_e32 v7, v39
	v_mov_b32_e32 v8, v40
	v_mov_b32_e32 v9, v41
	v_mov_b32_e32 v10, v42
	v_mov_b32_e32 v11, v43
	v_mov_b32_e32 v12, v44
	v_mov_b32_e32 v13, v45
	v_mov_b32_e32 v14, v50
	v_mov_b32_e32 v15, v51
	v_mov_b32_e32 v16, v52
	v_mov_b32_e32 v17, v53
	v_mov_b32_e32 v18, v46
	v_mov_b32_e32 v19, v47
	v_mov_b32_e32 v20, v48
	v_mov_b32_e32 v21, v49
	v_mov_b32_e32 v22, v54
	v_mov_b32_e32 v23, v55
	v_mov_b32_e32 v24, v56
	v_mov_b32_e32 v25, v57
	v_mov_b32_e32 v26, v58
	v_mov_b32_e32 v27, v59
	v_mov_b32_e32 v28, v60
	v_mov_b32_e32 v29, v61
	v_mov_b32_e32 v30, v62
	v_mov_b32_e32 v31, v63
	v_mov_b32_e32 v32, v64
	v_mov_b32_e32 v33, v65
	s_andn2_b64 exec, exec, s[34:35]
	s_cbranch_execz .LBB2_165

.LBB2_469:
	s_lshl_b32 s11, s74, 2
	s_add_i32 s11, s71, s11
	s_mul_i32 s16, s11, 0xc0
	s_and_b64 vcc, exec, s[8:9]
	v_lshlrev_b32_e32 v166, 1, v142
	s_cbranch_vccz .LBB2_471
	v_lshlrev_b64 v[130:131], 8, v[168:169]
	v_lshl_add_u64 v[156:157], v[160:161], 0, v[130:131]
	flat_load_dwordx4 v[130:133], v[156:157] offset:48
	flat_load_dwordx4 v[242:245], v[156:157] offset:16
	flat_load_dwordx4 v[246:249], v[156:157]
	flat_load_dwordx4 v[176:179], v[156:157] offset:32
	v_mov_b32_e32 v158, v116
	v_mov_b32_e32 v159, v124
	v_pk_mul_f32 v[158:159], v[158:159], v[170:171] op_sel_hi:[1,0]
	v_mov_b32_e32 v124, v117
	s_movk_i32 s8, 0xc00
	s_waitcnt vmcnt(0) lgkmcnt(0)
	v_pk_mul_f32 v[172:173], v[158:159], v[130:131]
	v_pk_mul_f32 v[130:131], v[158:159], v[130:131] op_sel:[1,0] op_sel_hi:[0,1]
	v_sub_f32_e32 v167, v130, v131
	v_mov_b32_e32 v130, v115
	v_mov_b32_e32 v131, v123
	v_mov_b32_e32 v115, v122
	v_pk_mul_f32 v[130:131], v[130:131], v[170:171] op_sel_hi:[1,0]
	v_pk_mul_f32 v[114:115], v[114:115], v[170:171] op_sel_hi:[1,0]
	v_pk_mul_f32 v[158:159], v[130:131], v[178:179]
	v_pk_mul_f32 v[130:131], v[130:131], v[178:179] op_sel:[1,0] op_sel_hi:[0,1]
	v_pk_mul_f32 v[122:123], v[114:115], v[176:177]
	v_pk_mul_f32 v[114:115], v[114:115], v[176:177] op_sel:[1,0] op_sel_hi:[0,1]
	v_mov_b32_e32 v176, v242
	v_mov_b32_e32 v177, v243
	v_mov_b32_e32 v178, v244
	v_mov_b32_e32 v179, v245
	v_add_f32_e32 v158, v158, v159
	v_sub_f32_e32 v159, v114, v115
	v_mov_b32_e32 v114, v121
	v_mov_b32_e32 v115, v129
	v_pk_mul_f32 v[114:115], v[114:115], v[170:171] op_sel_hi:[1,0]
	v_sub_f32_e32 v130, v130, v131
	v_add_f32_e32 v131, v122, v123
	v_mov_b32_e32 v121, v128
	v_add_f32_e32 v0, v172, v173
	s_waitcnt vmcnt(0) lgkmcnt(0)
	v_pk_mul_f32 v[122:123], v[114:115], v[178:179]
	v_pk_mul_f32 v[114:115], v[114:115], v[178:179] op_sel:[1,0] op_sel_hi:[0,1]
	v_sub_f32_e32 v171, v114, v115
	v_pk_mul_f32 v[114:115], v[120:121], v[170:171] op_sel_hi:[1,0]
	v_add_f32_e32 v169, v122, v123
	v_pk_mul_f32 v[120:121], v[114:115], v[176:177]
	v_pk_mul_f32 v[114:115], v[114:115], v[176:177] op_sel:[1,0] op_sel_hi:[0,1]
	v_add_f32_e32 v172, v120, v121
	v_mov_b32_e32 v120, v246
	v_mov_b32_e32 v121, v247
	v_mov_b32_e32 v122, v248
	v_mov_b32_e32 v123, v249
	v_sub_f32_e32 v173, v114, v115
	v_mov_b32_e32 v114, v119
	v_mov_b32_e32 v115, v127
	v_pk_mul_f32 v[114:115], v[114:115], v[170:171] op_sel_hi:[1,0]
	v_mov_b32_e32 v119, v126
	s_waitcnt vmcnt(0) lgkmcnt(0)
	v_pk_mul_f32 v[128:129], v[114:115], v[122:123]
	v_pk_mul_f32 v[114:115], v[114:115], v[122:123] op_sel:[1,0] op_sel_hi:[0,1]
	v_sub_f32_e32 v122, v114, v115
	v_pk_mul_f32 v[114:115], v[118:119], v[170:171] op_sel_hi:[1,0]
	v_add_f32_e32 v127, v128, v129
	v_pk_mul_f32 v[118:119], v[114:115], v[120:121]
	v_pk_mul_f32 v[114:115], v[114:115], v[120:121] op_sel:[1,0] op_sel_hi:[0,1]
	v_add_f32_e32 v118, v118, v119
	v_sub_f32_e32 v119, v114, v115
	v_pk_mul_f32 v[114:115], v[124:125], v[170:171] op_sel_hi:[1,0]
	s_nop 0
	v_pk_mul_f32 v[116:117], v[114:115], v[132:133] op_sel:[1,0] op_sel_hi:[0,1]
	v_pk_mul_f32 v[114:115], v[114:115], v[132:133]
	v_sub_f32_e32 v117, v116, v117
	v_add_f32_e32 v121, v114, v115
	v_cvt_pk_bf16_f32 v114, v119, v122
	v_mov_b64_e32 v[122:123], s[6:7]
	v_mad_i64_i32 v[122:123], s[8:9], v168, s8, v[122:123]
	v_cvt_pk_bf16_f32 v115, v173, v171
	v_cvt_pk_bf16_f32 v116, v159, v130
	v_cvt_pk_bf16_f32 v117, v167, v117
	v_lshl_add_u64 v[122:123], s[16:17], 1, v[122:123]
	v_mov_b32_e32 v167, v1
	v_lshl_add_u64 v[122:123], v[122:123], 0, v[166:167]
	v_cvt_pk_bf16_f32 v118, v118, v127
	v_cvt_pk_bf16_f32 v119, v172, v169
	v_cvt_pk_bf16_f32 v120, v131, v158
	v_cvt_pk_bf16_f32 v121, v0, v121
	flat_store_dwordx4 v[122:123], v[114:117] offset:256
	flat_store_dwordx4 v[122:123], v[118:121] offset:320

.LBB2_489:
	s_and_b64 vcc, exec, s[8:9]
	s_cbranch_vccz .LBB2_491
	v_lshlrev_b64 v[114:115], 8, v[118:119]
	v_lshl_add_u64 v[126:127], v[160:161], 0, v[114:115]
	flat_load_dwordx4 v[114:117], v[126:127] offset:48
	flat_load_dwordx4 v[238:241], v[126:127] offset:32
	flat_load_dwordx4 v[242:245], v[126:127] offset:16
	flat_load_dwordx4 v[246:249], v[126:127]
	v_mov_b32_e32 v122, v100
	v_mov_b32_e32 v123, v108
	v_pk_mul_f32 v[122:123], v[122:123], v[120:121] op_sel_hi:[1,0]
	v_mov_b32_e32 v108, v101
	v_mov_b32_e32 v167, v1
	s_waitcnt vmcnt(0) lgkmcnt(0)
	v_pk_mul_f32 v[124:125], v[122:123], v[114:115]
	s_nop 0
	v_add_f32_e32 v0, v124, v125
	v_pk_mul_f32 v[114:115], v[122:123], v[114:115] op_sel:[1,0] op_sel_hi:[0,1]
	v_mov_b32_e32 v122, v238
	v_mov_b32_e32 v123, v239
	v_mov_b32_e32 v124, v240
	v_mov_b32_e32 v125, v241
	v_sub_f32_e32 v119, v114, v115
	v_mov_b32_e32 v114, v99
	v_mov_b32_e32 v115, v107
	v_pk_mul_f32 v[114:115], v[114:115], v[120:121] op_sel_hi:[1,0]
	v_mov_b32_e32 v99, v106
	s_waitcnt vmcnt(0) lgkmcnt(0)
	v_pk_mul_f32 v[128:129], v[114:115], v[124:125]
	s_nop 0
	v_add_f32_e32 v121, v128, v129
	v_pk_mul_f32 v[98:99], v[98:99], v[120:121] op_sel_hi:[1,0]
	v_pk_mul_f32 v[114:115], v[114:115], v[124:125] op_sel:[1,0] op_sel_hi:[0,1]
	v_pk_mul_f32 v[106:107], v[98:99], v[122:123]
	v_pk_mul_f32 v[98:99], v[98:99], v[122:123] op_sel:[1,0] op_sel_hi:[0,1]
	v_mov_b32_e32 v122, v242
	v_mov_b32_e32 v123, v243
	v_mov_b32_e32 v124, v244
	v_mov_b32_e32 v125, v245
	v_sub_f32_e32 v128, v98, v99
	v_mov_b32_e32 v98, v105
	v_mov_b32_e32 v99, v113
	v_pk_mul_f32 v[98:99], v[98:99], v[120:121] op_sel_hi:[1,0]
	v_sub_f32_e32 v114, v114, v115
	v_add_f32_e32 v115, v106, v107
	v_mov_b32_e32 v105, v112
	s_waitcnt vmcnt(0) lgkmcnt(0)
	v_pk_mul_f32 v[106:107], v[98:99], v[124:125]
	v_pk_mul_f32 v[98:99], v[98:99], v[124:125] op_sel:[1,0] op_sel_hi:[0,1]
	v_sub_f32_e32 v124, v98, v99
	v_pk_mul_f32 v[98:99], v[104:105], v[120:121] op_sel_hi:[1,0]
	v_add_f32_e32 v129, v106, v107
	v_pk_mul_f32 v[104:105], v[98:99], v[122:123]
	v_pk_mul_f32 v[98:99], v[98:99], v[122:123] op_sel:[1,0] op_sel_hi:[0,1]
	v_add_f32_e32 v125, v104, v105
	v_mov_b32_e32 v104, v246
	v_mov_b32_e32 v105, v247
	v_mov_b32_e32 v106, v248
	v_mov_b32_e32 v107, v249
	v_sub_f32_e32 v122, v98, v99
	v_mov_b32_e32 v98, v103
	v_mov_b32_e32 v99, v111
	v_pk_mul_f32 v[98:99], v[98:99], v[120:121] op_sel_hi:[1,0]
	v_mov_b32_e32 v103, v110
	s_waitcnt vmcnt(0) lgkmcnt(0)
	v_pk_mul_f32 v[112:113], v[98:99], v[106:107]
	v_pk_mul_f32 v[98:99], v[98:99], v[106:107] op_sel:[1,0] op_sel_hi:[0,1]
	v_sub_f32_e32 v106, v98, v99
	v_pk_mul_f32 v[98:99], v[102:103], v[120:121] op_sel_hi:[1,0]
	v_add_f32_e32 v111, v112, v113
	v_pk_mul_f32 v[102:103], v[98:99], v[104:105]
	v_pk_mul_f32 v[98:99], v[98:99], v[104:105] op_sel:[1,0] op_sel_hi:[0,1]
	v_add_f32_e32 v102, v102, v103
	v_sub_f32_e32 v103, v98, v99
	v_pk_mul_f32 v[98:99], v[108:109], v[120:121] op_sel_hi:[1,0]
	s_nop 0
	v_pk_mul_f32 v[100:101], v[98:99], v[116:117] op_sel:[1,0] op_sel_hi:[0,1]
	v_pk_mul_f32 v[98:99], v[98:99], v[116:117]
	v_sub_f32_e32 v101, v100, v101
	v_add_f32_e32 v105, v98, v99
	v_cvt_pk_bf16_f32 v98, v103, v106
	v_mov_b64_e32 v[106:107], s[6:7]
	v_mad_i64_i32 v[106:107], s[0:1], v118, s2, v[106:107]
	v_lshl_add_u64 v[106:107], s[16:17], 1, v[106:107]
	v_cvt_pk_bf16_f32 v99, v122, v124
	v_cvt_pk_bf16_f32 v100, v128, v114
	v_cvt_pk_bf16_f32 v101, v119, v101
	v_lshl_add_u64 v[106:107], v[106:107], 0, v[166:167]
	v_cvt_pk_bf16_f32 v102, v102, v111
	v_cvt_pk_bf16_f32 v103, v125, v129
	v_cvt_pk_bf16_f32 v104, v115, v121
	v_cvt_pk_bf16_f32 v105, v0, v105
	flat_store_dwordx4 v[106:107], v[98:101] offset:256
	flat_store_dwordx4 v[106:107], v[102:105] offset:320

.LBB2_509:
	s_and_b64 vcc, exec, s[0:1]
	s_cbranch_vccz .LBB2_511
	v_lshlrev_b64 v[98:99], 8, v[102:103]
	v_lshl_add_u64 v[110:111], v[160:161], 0, v[98:99]
	flat_load_dwordx4 v[98:101], v[110:111] offset:48
	flat_load_dwordx4 v[238:241], v[110:111] offset:32
	flat_load_dwordx4 v[242:245], v[110:111] offset:16
	flat_load_dwordx4 v[246:249], v[110:111]
	v_mov_b32_e32 v106, v84
	v_mov_b32_e32 v107, v92
	v_pk_mul_f32 v[106:107], v[106:107], v[104:105] op_sel_hi:[1,0]
	v_mov_b32_e32 v92, v85
	v_mov_b32_e32 v167, v1
	s_waitcnt vmcnt(0) lgkmcnt(0)
	v_pk_mul_f32 v[108:109], v[106:107], v[98:99]
	s_nop 0
	v_add_f32_e32 v0, v108, v109
	v_pk_mul_f32 v[98:99], v[106:107], v[98:99] op_sel:[1,0] op_sel_hi:[0,1]
	v_mov_b32_e32 v106, v238
	v_mov_b32_e32 v107, v239
	v_mov_b32_e32 v108, v240
	v_mov_b32_e32 v109, v241
	v_sub_f32_e32 v103, v98, v99
	v_mov_b32_e32 v98, v83
	v_mov_b32_e32 v99, v91
	v_pk_mul_f32 v[98:99], v[98:99], v[104:105] op_sel_hi:[1,0]
	v_mov_b32_e32 v83, v90
	s_waitcnt vmcnt(0) lgkmcnt(0)
	v_pk_mul_f32 v[112:113], v[98:99], v[108:109]
	s_nop 0
	v_add_f32_e32 v105, v112, v113
	v_pk_mul_f32 v[82:83], v[82:83], v[104:105] op_sel_hi:[1,0]
	v_pk_mul_f32 v[98:99], v[98:99], v[108:109] op_sel:[1,0] op_sel_hi:[0,1]
	v_pk_mul_f32 v[90:91], v[82:83], v[106:107]
	v_pk_mul_f32 v[82:83], v[82:83], v[106:107] op_sel:[1,0] op_sel_hi:[0,1]
	v_mov_b32_e32 v106, v242
	v_mov_b32_e32 v107, v243
	v_mov_b32_e32 v108, v244
	v_mov_b32_e32 v109, v245
	v_sub_f32_e32 v112, v82, v83
	v_mov_b32_e32 v82, v89
	v_mov_b32_e32 v83, v97
	v_pk_mul_f32 v[82:83], v[82:83], v[104:105] op_sel_hi:[1,0]
	v_sub_f32_e32 v98, v98, v99
	v_add_f32_e32 v99, v90, v91
	v_mov_b32_e32 v89, v96
	s_waitcnt vmcnt(0) lgkmcnt(0)
	v_pk_mul_f32 v[90:91], v[82:83], v[108:109]
	v_pk_mul_f32 v[82:83], v[82:83], v[108:109] op_sel:[1,0] op_sel_hi:[0,1]
	v_sub_f32_e32 v108, v82, v83
	v_pk_mul_f32 v[82:83], v[88:89], v[104:105] op_sel_hi:[1,0]
	v_add_f32_e32 v113, v90, v91
	v_pk_mul_f32 v[88:89], v[82:83], v[106:107]
	v_pk_mul_f32 v[82:83], v[82:83], v[106:107] op_sel:[1,0] op_sel_hi:[0,1]
	v_add_f32_e32 v109, v88, v89
	v_mov_b32_e32 v88, v246
	v_mov_b32_e32 v89, v247
	v_mov_b32_e32 v90, v248
	v_mov_b32_e32 v91, v249
	v_sub_f32_e32 v106, v82, v83
	v_mov_b32_e32 v82, v87
	v_mov_b32_e32 v83, v95
	v_pk_mul_f32 v[82:83], v[82:83], v[104:105] op_sel_hi:[1,0]
	v_mov_b32_e32 v87, v94
	s_waitcnt vmcnt(0) lgkmcnt(0)
	v_pk_mul_f32 v[96:97], v[82:83], v[90:91]
	v_pk_mul_f32 v[82:83], v[82:83], v[90:91] op_sel:[1,0] op_sel_hi:[0,1]
	v_sub_f32_e32 v90, v82, v83
	v_pk_mul_f32 v[82:83], v[86:87], v[104:105] op_sel_hi:[1,0]
	v_add_f32_e32 v95, v96, v97
	v_pk_mul_f32 v[86:87], v[82:83], v[88:89]
	v_pk_mul_f32 v[82:83], v[82:83], v[88:89] op_sel:[1,0] op_sel_hi:[0,1]
	v_add_f32_e32 v86, v86, v87
	v_sub_f32_e32 v87, v82, v83
	v_pk_mul_f32 v[82:83], v[92:93], v[104:105] op_sel_hi:[1,0]
	s_nop 0
	v_pk_mul_f32 v[84:85], v[82:83], v[100:101] op_sel:[1,0] op_sel_hi:[0,1]
	v_pk_mul_f32 v[82:83], v[82:83], v[100:101]
	v_sub_f32_e32 v85, v84, v85
	v_add_f32_e32 v89, v82, v83
	v_cvt_pk_bf16_f32 v82, v87, v90
	v_mov_b64_e32 v[90:91], s[6:7]
	v_mad_i64_i32 v[90:91], s[0:1], v102, s2, v[90:91]
	v_lshl_add_u64 v[90:91], s[16:17], 1, v[90:91]
	v_cvt_pk_bf16_f32 v83, v106, v108
	v_cvt_pk_bf16_f32 v84, v112, v98
	v_cvt_pk_bf16_f32 v85, v103, v85
	v_lshl_add_u64 v[90:91], v[90:91], 0, v[166:167]
	v_cvt_pk_bf16_f32 v86, v86, v95
	v_cvt_pk_bf16_f32 v87, v109, v113
	v_cvt_pk_bf16_f32 v88, v99, v105
	v_cvt_pk_bf16_f32 v89, v0, v89
	flat_store_dwordx4 v[90:91], v[82:85] offset:256
	flat_store_dwordx4 v[90:91], v[86:89] offset:320

.LBB2_529:
	s_and_b64 vcc, exec, s[0:1]
	s_cbranch_vccz .LBB2_531
	v_lshlrev_b64 v[82:83], 8, v[86:87]
	v_lshl_add_u64 v[94:95], v[160:161], 0, v[82:83]
	flat_load_dwordx4 v[82:85], v[94:95] offset:48
	flat_load_dwordx4 v[238:241], v[94:95] offset:32
	flat_load_dwordx4 v[242:245], v[94:95] offset:16
	flat_load_dwordx4 v[246:249], v[94:95]
	v_mov_b32_e32 v90, v68
	v_mov_b32_e32 v91, v76
	v_pk_mul_f32 v[90:91], v[90:91], v[88:89] op_sel_hi:[1,0]
	v_mov_b32_e32 v76, v69
	v_mov_b32_e32 v167, v1
	s_waitcnt vmcnt(0) lgkmcnt(0)
	v_pk_mul_f32 v[92:93], v[90:91], v[82:83]
	s_nop 0
	v_add_f32_e32 v0, v92, v93
	v_pk_mul_f32 v[82:83], v[90:91], v[82:83] op_sel:[1,0] op_sel_hi:[0,1]
	v_mov_b32_e32 v90, v238
	v_mov_b32_e32 v91, v239
	v_mov_b32_e32 v92, v240
	v_mov_b32_e32 v93, v241
	v_sub_f32_e32 v87, v82, v83
	v_mov_b32_e32 v82, v67
	v_mov_b32_e32 v83, v75
	v_pk_mul_f32 v[82:83], v[82:83], v[88:89] op_sel_hi:[1,0]
	v_mov_b32_e32 v67, v74
	s_waitcnt vmcnt(0) lgkmcnt(0)
	v_pk_mul_f32 v[96:97], v[82:83], v[92:93]
	s_nop 0
	v_add_f32_e32 v89, v96, v97
	v_pk_mul_f32 v[66:67], v[66:67], v[88:89] op_sel_hi:[1,0]
	v_pk_mul_f32 v[82:83], v[82:83], v[92:93] op_sel:[1,0] op_sel_hi:[0,1]
	v_pk_mul_f32 v[74:75], v[66:67], v[90:91]
	v_pk_mul_f32 v[66:67], v[66:67], v[90:91] op_sel:[1,0] op_sel_hi:[0,1]
	v_mov_b32_e32 v90, v242
	v_mov_b32_e32 v91, v243
	v_mov_b32_e32 v92, v244
	v_mov_b32_e32 v93, v245
	v_sub_f32_e32 v96, v66, v67
	v_mov_b32_e32 v66, v73
	v_mov_b32_e32 v67, v81
	v_pk_mul_f32 v[66:67], v[66:67], v[88:89] op_sel_hi:[1,0]
	v_sub_f32_e32 v82, v82, v83
	v_add_f32_e32 v83, v74, v75
	v_mov_b32_e32 v73, v80
	s_waitcnt vmcnt(0) lgkmcnt(0)
	v_pk_mul_f32 v[74:75], v[66:67], v[92:93]
	v_pk_mul_f32 v[66:67], v[66:67], v[92:93] op_sel:[1,0] op_sel_hi:[0,1]
	v_sub_f32_e32 v92, v66, v67
	v_pk_mul_f32 v[66:67], v[72:73], v[88:89] op_sel_hi:[1,0]
	v_add_f32_e32 v97, v74, v75
	v_pk_mul_f32 v[72:73], v[66:67], v[90:91]
	v_pk_mul_f32 v[66:67], v[66:67], v[90:91] op_sel:[1,0] op_sel_hi:[0,1]
	v_add_f32_e32 v93, v72, v73
	v_mov_b32_e32 v72, v246
	v_mov_b32_e32 v73, v247
	v_mov_b32_e32 v74, v248
	v_mov_b32_e32 v75, v249
	v_sub_f32_e32 v90, v66, v67
	v_mov_b32_e32 v66, v71
	v_mov_b32_e32 v67, v79
	v_pk_mul_f32 v[66:67], v[66:67], v[88:89] op_sel_hi:[1,0]
	v_mov_b32_e32 v71, v78
	s_waitcnt vmcnt(0) lgkmcnt(0)
	v_pk_mul_f32 v[80:81], v[66:67], v[74:75]
	v_pk_mul_f32 v[66:67], v[66:67], v[74:75] op_sel:[1,0] op_sel_hi:[0,1]
	v_sub_f32_e32 v74, v66, v67
	v_pk_mul_f32 v[66:67], v[70:71], v[88:89] op_sel_hi:[1,0]
	v_add_f32_e32 v79, v80, v81
	v_pk_mul_f32 v[70:71], v[66:67], v[72:73]
	v_pk_mul_f32 v[66:67], v[66:67], v[72:73] op_sel:[1,0] op_sel_hi:[0,1]
	v_add_f32_e32 v70, v70, v71
	v_sub_f32_e32 v71, v66, v67
	v_pk_mul_f32 v[66:67], v[76:77], v[88:89] op_sel_hi:[1,0]
	s_nop 0
	v_pk_mul_f32 v[68:69], v[66:67], v[84:85] op_sel:[1,0] op_sel_hi:[0,1]
	v_pk_mul_f32 v[66:67], v[66:67], v[84:85]
	v_sub_f32_e32 v69, v68, v69
	v_add_f32_e32 v73, v66, v67
	v_cvt_pk_bf16_f32 v66, v71, v74
	v_mov_b64_e32 v[74:75], s[6:7]
	v_mad_i64_i32 v[74:75], s[0:1], v86, s2, v[74:75]
	v_lshl_add_u64 v[74:75], s[16:17], 1, v[74:75]
	v_cvt_pk_bf16_f32 v67, v90, v92
	v_cvt_pk_bf16_f32 v68, v96, v82
	v_cvt_pk_bf16_f32 v69, v87, v69
	v_lshl_add_u64 v[74:75], v[74:75], 0, v[166:167]
	v_cvt_pk_bf16_f32 v70, v70, v79
	v_cvt_pk_bf16_f32 v71, v93, v97
	v_cvt_pk_bf16_f32 v72, v83, v89
	v_cvt_pk_bf16_f32 v73, v0, v73
	flat_store_dwordx4 v[74:75], v[66:69] offset:256
	flat_store_dwordx4 v[74:75], v[70:73] offset:320

.LBB2_549:
	s_and_b64 vcc, exec, s[0:1]
	s_cbranch_vccz .LBB2_551
	v_lshlrev_b64 v[66:67], 8, v[70:71]
	v_lshl_add_u64 v[78:79], v[160:161], 0, v[66:67]
	flat_load_dwordx4 v[66:69], v[78:79] offset:48
	flat_load_dwordx4 v[238:241], v[78:79] offset:32
	flat_load_dwordx4 v[242:245], v[78:79] offset:16
	flat_load_dwordx4 v[246:249], v[78:79]
	v_mov_b32_e32 v74, v52
	v_mov_b32_e32 v75, v60
	v_pk_mul_f32 v[74:75], v[74:75], v[72:73] op_sel_hi:[1,0]
	v_mov_b32_e32 v60, v53
	v_mov_b32_e32 v167, v1
	s_waitcnt vmcnt(0) lgkmcnt(0)
	v_pk_mul_f32 v[76:77], v[74:75], v[66:67]
	s_nop 0
	v_add_f32_e32 v0, v76, v77
	v_pk_mul_f32 v[66:67], v[74:75], v[66:67] op_sel:[1,0] op_sel_hi:[0,1]
	v_mov_b32_e32 v74, v238
	v_mov_b32_e32 v75, v239
	v_mov_b32_e32 v76, v240
	v_mov_b32_e32 v77, v241
	v_sub_f32_e32 v71, v66, v67
	v_mov_b32_e32 v66, v51
	v_mov_b32_e32 v67, v59
	v_pk_mul_f32 v[66:67], v[66:67], v[72:73] op_sel_hi:[1,0]
	v_mov_b32_e32 v51, v58
	s_waitcnt vmcnt(0) lgkmcnt(0)
	v_pk_mul_f32 v[80:81], v[66:67], v[76:77]
	s_nop 0
	v_add_f32_e32 v73, v80, v81
	v_pk_mul_f32 v[50:51], v[50:51], v[72:73] op_sel_hi:[1,0]
	v_pk_mul_f32 v[66:67], v[66:67], v[76:77] op_sel:[1,0] op_sel_hi:[0,1]
	v_pk_mul_f32 v[58:59], v[50:51], v[74:75]
	v_pk_mul_f32 v[50:51], v[50:51], v[74:75] op_sel:[1,0] op_sel_hi:[0,1]
	v_mov_b32_e32 v74, v242
	v_mov_b32_e32 v75, v243
	v_mov_b32_e32 v76, v244
	v_mov_b32_e32 v77, v245
	v_sub_f32_e32 v80, v50, v51
	v_mov_b32_e32 v50, v57
	v_mov_b32_e32 v51, v65
	v_pk_mul_f32 v[50:51], v[50:51], v[72:73] op_sel_hi:[1,0]
	v_sub_f32_e32 v66, v66, v67
	v_add_f32_e32 v67, v58, v59
	v_mov_b32_e32 v57, v64
	s_waitcnt vmcnt(0) lgkmcnt(0)
	v_pk_mul_f32 v[58:59], v[50:51], v[76:77]
	v_pk_mul_f32 v[50:51], v[50:51], v[76:77] op_sel:[1,0] op_sel_hi:[0,1]
	v_sub_f32_e32 v76, v50, v51
	v_pk_mul_f32 v[50:51], v[56:57], v[72:73] op_sel_hi:[1,0]
	v_add_f32_e32 v81, v58, v59
	v_pk_mul_f32 v[56:57], v[50:51], v[74:75]
	v_pk_mul_f32 v[50:51], v[50:51], v[74:75] op_sel:[1,0] op_sel_hi:[0,1]
	v_add_f32_e32 v77, v56, v57
	v_mov_b32_e32 v56, v246
	v_mov_b32_e32 v57, v247
	v_mov_b32_e32 v58, v248
	v_mov_b32_e32 v59, v249
	v_sub_f32_e32 v74, v50, v51
	v_mov_b32_e32 v50, v55
	v_mov_b32_e32 v51, v63
	v_pk_mul_f32 v[50:51], v[50:51], v[72:73] op_sel_hi:[1,0]
	v_mov_b32_e32 v55, v62
	s_waitcnt vmcnt(0) lgkmcnt(0)
	v_pk_mul_f32 v[64:65], v[50:51], v[58:59]
	v_pk_mul_f32 v[50:51], v[50:51], v[58:59] op_sel:[1,0] op_sel_hi:[0,1]
	v_sub_f32_e32 v58, v50, v51
	v_pk_mul_f32 v[50:51], v[54:55], v[72:73] op_sel_hi:[1,0]
	v_add_f32_e32 v63, v64, v65
	v_pk_mul_f32 v[54:55], v[50:51], v[56:57]
	v_pk_mul_f32 v[50:51], v[50:51], v[56:57] op_sel:[1,0] op_sel_hi:[0,1]
	v_add_f32_e32 v54, v54, v55
	v_sub_f32_e32 v55, v50, v51
	v_pk_mul_f32 v[50:51], v[60:61], v[72:73] op_sel_hi:[1,0]
	s_nop 0
	v_pk_mul_f32 v[52:53], v[50:51], v[68:69] op_sel:[1,0] op_sel_hi:[0,1]
	v_pk_mul_f32 v[50:51], v[50:51], v[68:69]
	v_sub_f32_e32 v53, v52, v53
	v_add_f32_e32 v57, v50, v51
	v_cvt_pk_bf16_f32 v50, v55, v58
	v_mov_b64_e32 v[58:59], s[6:7]
	v_mad_i64_i32 v[58:59], s[0:1], v70, s2, v[58:59]
	v_lshl_add_u64 v[58:59], s[16:17], 1, v[58:59]
	v_cvt_pk_bf16_f32 v51, v74, v76
	v_cvt_pk_bf16_f32 v52, v80, v66
	v_cvt_pk_bf16_f32 v53, v71, v53
	v_lshl_add_u64 v[58:59], v[58:59], 0, v[166:167]
	v_cvt_pk_bf16_f32 v54, v54, v63
	v_cvt_pk_bf16_f32 v55, v77, v81
	v_cvt_pk_bf16_f32 v56, v67, v73
	v_cvt_pk_bf16_f32 v57, v0, v57
	flat_store_dwordx4 v[58:59], v[50:53] offset:256
	flat_store_dwordx4 v[58:59], v[54:57] offset:320

.LBB2_569:
	s_and_b64 vcc, exec, s[0:1]
	s_cbranch_vccz .LBB2_571
	v_lshlrev_b64 v[50:51], 8, v[54:55]
	v_lshl_add_u64 v[62:63], v[160:161], 0, v[50:51]
	flat_load_dwordx4 v[50:53], v[62:63] offset:48
	flat_load_dwordx4 v[238:241], v[62:63] offset:32
	flat_load_dwordx4 v[242:245], v[62:63] offset:16
	flat_load_dwordx4 v[246:249], v[62:63]
	v_mov_b32_e32 v58, v36
	v_mov_b32_e32 v59, v44
	v_pk_mul_f32 v[58:59], v[58:59], v[56:57] op_sel_hi:[1,0]
	v_mov_b32_e32 v44, v37
	v_mov_b32_e32 v167, v1
	s_waitcnt vmcnt(0) lgkmcnt(0)
	v_pk_mul_f32 v[60:61], v[58:59], v[50:51]
	s_nop 0
	v_add_f32_e32 v0, v60, v61
	v_pk_mul_f32 v[50:51], v[58:59], v[50:51] op_sel:[1,0] op_sel_hi:[0,1]
	v_mov_b32_e32 v58, v238
	v_mov_b32_e32 v59, v239
	v_mov_b32_e32 v60, v240
	v_mov_b32_e32 v61, v241
	v_sub_f32_e32 v55, v50, v51
	v_mov_b32_e32 v50, v35
	v_mov_b32_e32 v51, v43
	v_pk_mul_f32 v[50:51], v[50:51], v[56:57] op_sel_hi:[1,0]
	v_mov_b32_e32 v35, v42
	s_waitcnt vmcnt(0) lgkmcnt(0)
	v_pk_mul_f32 v[64:65], v[50:51], v[60:61]
	s_nop 0
	v_add_f32_e32 v57, v64, v65
	v_pk_mul_f32 v[34:35], v[34:35], v[56:57] op_sel_hi:[1,0]
	v_pk_mul_f32 v[50:51], v[50:51], v[60:61] op_sel:[1,0] op_sel_hi:[0,1]
	v_pk_mul_f32 v[42:43], v[34:35], v[58:59]
	v_pk_mul_f32 v[34:35], v[34:35], v[58:59] op_sel:[1,0] op_sel_hi:[0,1]
	v_mov_b32_e32 v58, v242
	v_mov_b32_e32 v59, v243
	v_mov_b32_e32 v60, v244
	v_mov_b32_e32 v61, v245
	v_sub_f32_e32 v64, v34, v35
	v_mov_b32_e32 v34, v41
	v_mov_b32_e32 v35, v49
	v_pk_mul_f32 v[34:35], v[34:35], v[56:57] op_sel_hi:[1,0]
	v_sub_f32_e32 v50, v50, v51
	v_add_f32_e32 v51, v42, v43
	v_mov_b32_e32 v41, v48
	s_waitcnt vmcnt(0) lgkmcnt(0)
	v_pk_mul_f32 v[42:43], v[34:35], v[60:61]
	v_pk_mul_f32 v[34:35], v[34:35], v[60:61] op_sel:[1,0] op_sel_hi:[0,1]
	v_sub_f32_e32 v60, v34, v35
	v_pk_mul_f32 v[34:35], v[40:41], v[56:57] op_sel_hi:[1,0]
	v_add_f32_e32 v65, v42, v43
	v_pk_mul_f32 v[40:41], v[34:35], v[58:59]
	v_pk_mul_f32 v[34:35], v[34:35], v[58:59] op_sel:[1,0] op_sel_hi:[0,1]
	v_add_f32_e32 v61, v40, v41
	v_mov_b32_e32 v40, v246
	v_mov_b32_e32 v41, v247
	v_mov_b32_e32 v42, v248
	v_mov_b32_e32 v43, v249
	v_sub_f32_e32 v58, v34, v35
	v_mov_b32_e32 v34, v39
	v_mov_b32_e32 v35, v47
	v_pk_mul_f32 v[34:35], v[34:35], v[56:57] op_sel_hi:[1,0]
	v_mov_b32_e32 v39, v46
	s_waitcnt vmcnt(0) lgkmcnt(0)
	v_pk_mul_f32 v[48:49], v[34:35], v[42:43]
	v_pk_mul_f32 v[34:35], v[34:35], v[42:43] op_sel:[1,0] op_sel_hi:[0,1]
	v_sub_f32_e32 v42, v34, v35
	v_pk_mul_f32 v[34:35], v[38:39], v[56:57] op_sel_hi:[1,0]
	v_add_f32_e32 v47, v48, v49
	v_pk_mul_f32 v[38:39], v[34:35], v[40:41]
	v_pk_mul_f32 v[34:35], v[34:35], v[40:41] op_sel:[1,0] op_sel_hi:[0,1]
	v_add_f32_e32 v38, v38, v39
	v_sub_f32_e32 v39, v34, v35
	v_pk_mul_f32 v[34:35], v[44:45], v[56:57] op_sel_hi:[1,0]
	s_nop 0
	v_pk_mul_f32 v[36:37], v[34:35], v[52:53] op_sel:[1,0] op_sel_hi:[0,1]
	v_pk_mul_f32 v[34:35], v[34:35], v[52:53]
	v_sub_f32_e32 v37, v36, v37
	v_add_f32_e32 v41, v34, v35
	v_cvt_pk_bf16_f32 v34, v39, v42
	v_mov_b64_e32 v[42:43], s[6:7]
	v_mad_i64_i32 v[42:43], s[0:1], v54, s2, v[42:43]
	v_lshl_add_u64 v[42:43], s[16:17], 1, v[42:43]
	v_cvt_pk_bf16_f32 v35, v58, v60
	v_cvt_pk_bf16_f32 v36, v64, v50
	v_cvt_pk_bf16_f32 v37, v55, v37
	v_lshl_add_u64 v[42:43], v[42:43], 0, v[166:167]
	v_cvt_pk_bf16_f32 v38, v38, v47
	v_cvt_pk_bf16_f32 v39, v61, v65
	v_cvt_pk_bf16_f32 v40, v51, v57
	v_cvt_pk_bf16_f32 v41, v0, v41
	flat_store_dwordx4 v[42:43], v[34:37] offset:256
	flat_store_dwordx4 v[42:43], v[38:41] offset:320

.LBB2_589:
	s_and_b64 vcc, exec, s[0:1]
	s_cbranch_vccz .LBB2_591
	v_lshlrev_b64 v[34:35], 8, v[38:39]
	v_lshl_add_u64 v[46:47], v[160:161], 0, v[34:35]
	flat_load_dwordx4 v[34:37], v[46:47] offset:48
	flat_load_dwordx4 v[238:241], v[46:47] offset:32
	flat_load_dwordx4 v[242:245], v[46:47] offset:16
	flat_load_dwordx4 v[246:249], v[46:47]
	v_mov_b32_e32 v42, v20
	v_mov_b32_e32 v43, v28
	v_pk_mul_f32 v[42:43], v[42:43], v[40:41] op_sel_hi:[1,0]
	v_mov_b32_e32 v28, v21
	v_mov_b32_e32 v167, v1
	s_waitcnt vmcnt(0) lgkmcnt(0)
	v_pk_mul_f32 v[44:45], v[42:43], v[34:35]
	s_nop 0
	v_add_f32_e32 v0, v44, v45
	v_pk_mul_f32 v[34:35], v[42:43], v[34:35] op_sel:[1,0] op_sel_hi:[0,1]
	v_mov_b32_e32 v42, v238
	v_mov_b32_e32 v43, v239
	v_mov_b32_e32 v44, v240
	v_mov_b32_e32 v45, v241
	v_sub_f32_e32 v39, v34, v35
	v_mov_b32_e32 v34, v19
	v_mov_b32_e32 v35, v27
	v_pk_mul_f32 v[34:35], v[34:35], v[40:41] op_sel_hi:[1,0]
	v_mov_b32_e32 v19, v26
	s_waitcnt vmcnt(0) lgkmcnt(0)
	v_pk_mul_f32 v[48:49], v[34:35], v[44:45]
	s_nop 0
	v_add_f32_e32 v41, v48, v49
	v_pk_mul_f32 v[18:19], v[18:19], v[40:41] op_sel_hi:[1,0]
	v_pk_mul_f32 v[34:35], v[34:35], v[44:45] op_sel:[1,0] op_sel_hi:[0,1]
	v_pk_mul_f32 v[26:27], v[18:19], v[42:43]
	v_pk_mul_f32 v[18:19], v[18:19], v[42:43] op_sel:[1,0] op_sel_hi:[0,1]
	v_mov_b32_e32 v42, v242
	v_mov_b32_e32 v43, v243
	v_mov_b32_e32 v44, v244
	v_mov_b32_e32 v45, v245
	v_sub_f32_e32 v48, v18, v19
	v_mov_b32_e32 v18, v25
	v_mov_b32_e32 v19, v33
	v_pk_mul_f32 v[18:19], v[18:19], v[40:41] op_sel_hi:[1,0]
	v_sub_f32_e32 v34, v34, v35
	v_add_f32_e32 v35, v26, v27
	v_mov_b32_e32 v25, v32
	s_waitcnt vmcnt(0) lgkmcnt(0)
	v_pk_mul_f32 v[26:27], v[18:19], v[44:45]
	v_pk_mul_f32 v[18:19], v[18:19], v[44:45] op_sel:[1,0] op_sel_hi:[0,1]
	v_sub_f32_e32 v44, v18, v19
	v_pk_mul_f32 v[18:19], v[24:25], v[40:41] op_sel_hi:[1,0]
	v_add_f32_e32 v49, v26, v27
	v_pk_mul_f32 v[24:25], v[18:19], v[42:43]
	v_pk_mul_f32 v[18:19], v[18:19], v[42:43] op_sel:[1,0] op_sel_hi:[0,1]
	v_add_f32_e32 v45, v24, v25
	v_mov_b32_e32 v24, v246
	v_mov_b32_e32 v25, v247
	v_mov_b32_e32 v26, v248
	v_mov_b32_e32 v27, v249
	v_sub_f32_e32 v42, v18, v19
	v_mov_b32_e32 v18, v23
	v_mov_b32_e32 v19, v31
	v_pk_mul_f32 v[18:19], v[18:19], v[40:41] op_sel_hi:[1,0]
	v_mov_b32_e32 v23, v30
	s_waitcnt vmcnt(0) lgkmcnt(0)
	v_pk_mul_f32 v[32:33], v[18:19], v[26:27]
	v_pk_mul_f32 v[18:19], v[18:19], v[26:27] op_sel:[1,0] op_sel_hi:[0,1]
	v_sub_f32_e32 v26, v18, v19
	v_pk_mul_f32 v[18:19], v[22:23], v[40:41] op_sel_hi:[1,0]
	v_add_f32_e32 v31, v32, v33
	v_pk_mul_f32 v[22:23], v[18:19], v[24:25]
	v_pk_mul_f32 v[18:19], v[18:19], v[24:25] op_sel:[1,0] op_sel_hi:[0,1]
	v_add_f32_e32 v22, v22, v23
	v_sub_f32_e32 v23, v18, v19
	v_pk_mul_f32 v[18:19], v[28:29], v[40:41] op_sel_hi:[1,0]
	s_nop 0
	v_pk_mul_f32 v[20:21], v[18:19], v[36:37] op_sel:[1,0] op_sel_hi:[0,1]
	v_pk_mul_f32 v[18:19], v[18:19], v[36:37]
	v_sub_f32_e32 v21, v20, v21
	v_add_f32_e32 v25, v18, v19
	v_cvt_pk_bf16_f32 v18, v23, v26
	v_mov_b64_e32 v[26:27], s[6:7]
	v_mad_i64_i32 v[26:27], s[0:1], v38, s2, v[26:27]
	v_lshl_add_u64 v[26:27], s[16:17], 1, v[26:27]
	v_cvt_pk_bf16_f32 v19, v42, v44
	v_cvt_pk_bf16_f32 v20, v48, v34
	v_cvt_pk_bf16_f32 v21, v39, v21
	v_lshl_add_u64 v[26:27], v[26:27], 0, v[166:167]
	v_cvt_pk_bf16_f32 v22, v22, v31
	v_cvt_pk_bf16_f32 v23, v45, v49
	v_cvt_pk_bf16_f32 v24, v35, v41
	v_cvt_pk_bf16_f32 v25, v0, v25
	flat_store_dwordx4 v[26:27], v[18:21] offset:256
	flat_store_dwordx4 v[26:27], v[22:25] offset:320

.LBB2_611:
	v_lshlrev_b64 v[18:19], 8, v[22:23]
	v_lshl_add_u64 v[30:31], v[160:161], 0, v[18:19]
	flat_load_dwordx4 v[18:21], v[30:31] offset:48
	flat_load_dwordx4 v[238:241], v[30:31] offset:32
	flat_load_dwordx4 v[242:245], v[30:31] offset:16
	flat_load_dwordx4 v[246:249], v[30:31]
	v_mov_b32_e32 v26, v4
	v_mov_b32_e32 v27, v12
	v_pk_mul_f32 v[26:27], v[26:27], v[24:25] op_sel_hi:[1,0]
	v_mov_b32_e32 v12, v5
	v_mov_b32_e32 v167, v1
	s_waitcnt vmcnt(0) lgkmcnt(0)
	v_pk_mul_f32 v[28:29], v[26:27], v[18:19]
	s_nop 0
	v_add_f32_e32 v0, v28, v29
	v_pk_mul_f32 v[18:19], v[26:27], v[18:19] op_sel:[1,0] op_sel_hi:[0,1]
	v_mov_b32_e32 v26, v238
	v_mov_b32_e32 v27, v239
	v_mov_b32_e32 v28, v240
	v_mov_b32_e32 v29, v241
	v_sub_f32_e32 v23, v18, v19
	v_mov_b32_e32 v18, v3
	v_mov_b32_e32 v19, v11
	v_pk_mul_f32 v[18:19], v[18:19], v[24:25] op_sel_hi:[1,0]
	v_mov_b32_e32 v3, v10
	s_waitcnt vmcnt(0) lgkmcnt(0)
	v_pk_mul_f32 v[32:33], v[18:19], v[28:29]
	s_nop 0
	v_add_f32_e32 v25, v32, v33
	v_pk_mul_f32 v[2:3], v[2:3], v[24:25] op_sel_hi:[1,0]
	v_pk_mul_f32 v[18:19], v[18:19], v[28:29] op_sel:[1,0] op_sel_hi:[0,1]
	v_pk_mul_f32 v[10:11], v[2:3], v[26:27]
	v_pk_mul_f32 v[2:3], v[2:3], v[26:27] op_sel:[1,0] op_sel_hi:[0,1]
	v_mov_b32_e32 v26, v242
	v_mov_b32_e32 v27, v243
	v_mov_b32_e32 v28, v244
	v_mov_b32_e32 v29, v245
	v_sub_f32_e32 v32, v2, v3
	v_mov_b32_e32 v2, v9
	v_mov_b32_e32 v3, v17
	v_pk_mul_f32 v[2:3], v[2:3], v[24:25] op_sel_hi:[1,0]
	v_sub_f32_e32 v18, v18, v19
	v_add_f32_e32 v19, v10, v11
	v_mov_b32_e32 v9, v16
	s_waitcnt vmcnt(0) lgkmcnt(0)
	v_pk_mul_f32 v[10:11], v[2:3], v[28:29]
	v_pk_mul_f32 v[2:3], v[2:3], v[28:29] op_sel:[1,0] op_sel_hi:[0,1]
	v_sub_f32_e32 v28, v2, v3
	v_pk_mul_f32 v[2:3], v[8:9], v[24:25] op_sel_hi:[1,0]
	v_add_f32_e32 v33, v10, v11
	v_pk_mul_f32 v[8:9], v[2:3], v[26:27]
	v_pk_mul_f32 v[2:3], v[2:3], v[26:27] op_sel:[1,0] op_sel_hi:[0,1]
	v_add_f32_e32 v29, v8, v9
	v_mov_b32_e32 v8, v246
	v_mov_b32_e32 v9, v247
	v_mov_b32_e32 v10, v248
	v_mov_b32_e32 v11, v249
	v_sub_f32_e32 v26, v2, v3
	v_mov_b32_e32 v2, v7
	v_mov_b32_e32 v3, v15
	v_pk_mul_f32 v[2:3], v[2:3], v[24:25] op_sel_hi:[1,0]
	v_mov_b32_e32 v7, v14
	s_waitcnt vmcnt(0) lgkmcnt(0)
	v_pk_mul_f32 v[16:17], v[2:3], v[10:11]
	v_pk_mul_f32 v[2:3], v[2:3], v[10:11] op_sel:[1,0] op_sel_hi:[0,1]
	v_sub_f32_e32 v10, v2, v3
	v_pk_mul_f32 v[2:3], v[6:7], v[24:25] op_sel_hi:[1,0]
	v_add_f32_e32 v15, v16, v17
	v_pk_mul_f32 v[6:7], v[2:3], v[8:9]
	v_pk_mul_f32 v[2:3], v[2:3], v[8:9] op_sel:[1,0] op_sel_hi:[0,1]
	v_add_f32_e32 v6, v6, v7
	v_sub_f32_e32 v7, v2, v3
	v_pk_mul_f32 v[2:3], v[12:13], v[24:25] op_sel_hi:[1,0]
	s_nop 0
	v_pk_mul_f32 v[4:5], v[2:3], v[20:21] op_sel:[1,0] op_sel_hi:[0,1]
	v_pk_mul_f32 v[2:3], v[2:3], v[20:21]
	v_sub_f32_e32 v5, v4, v5
	v_add_f32_e32 v9, v2, v3
	v_cvt_pk_bf16_f32 v2, v7, v10
	v_mov_b64_e32 v[10:11], s[6:7]
	v_mad_i64_i32 v[10:11], s[0:1], v22, s2, v[10:11]
	v_lshl_add_u64 v[10:11], s[16:17], 1, v[10:11]
	v_cvt_pk_bf16_f32 v3, v26, v28
	v_cvt_pk_bf16_f32 v4, v32, v18
	v_cvt_pk_bf16_f32 v5, v23, v5
	v_lshl_add_u64 v[10:11], v[10:11], 0, v[166:167]
	v_cvt_pk_bf16_f32 v6, v6, v15
	v_cvt_pk_bf16_f32 v7, v29, v33
	v_cvt_pk_bf16_f32 v8, v19, v25
	v_cvt_pk_bf16_f32 v9, v0, v9
	flat_store_dwordx4 v[10:11], v[2:5] offset:256
	flat_store_dwordx4 v[10:11], v[6:9] offset:320
	s_andn2_b64 vcc, exec, s[36:37]
	s_mov_b64 s[0:1], -1
	s_cbranch_vccnz .LBB2_444
